# v37 plus: an XCD's last arriver waits for the cross-XCD arrival counter to reach the barrier's target (>=) instead of the generation word added one round trip later
# baseline (speedup 1.0000x reference)
; __device__ __forceinline__ unsigned xb_ld(unsigned* p)              { return __hip_atomic_load(p, __ATOMIC_RELAXED, __HIP_MEMORY_SCOPE_AGENT); }
; __device__ __forceinline__ unsigned xb_add(unsigned* p, unsigned v) { return __hip_atomic_fetch_add(p, v, __ATOMIC_RELAXED, __HIP_MEMORY_SCOPE_AGENT); }
; #define XB_SPIN(cond, bar) do { unsigned _sp = 0; while (cond) { __builtin_amdgcn_s_sleep(1); \
;     if ((++_sp & 255u) == 0u) { if (xb_ld(&(bar)[XB_TMO])) break; if (_sp > XB_SPIN_CAP) { atomicAdd(&(bar)[XB_TMO], 1u); break; } } } } while (0)
; __device__ __forceinline__ void xcd_barrier(const XcdBarrier& b) {
;     ...
;             const unsigned og = xb_add(&bar[XB_TOP], 1u);
;             const unsigned tg = og / nx;
;             if (og + 1u == (tg + 1u) * nx) xb_add(&bar[XB_TOPGEN], 1u);
;             else XB_SPIN(xb_ld(&bar[XB_TOPGEN]) == tg, bar);
.LBB0_134:
	s_or_b64 exec, exec, s[14:15]
	v_cvt_f32_u32_e32 v3, v0
	s_waitcnt vmcnt(0)
	v_readfirstlane_b32 s12, v2
	s_add_u32 s14, s24, 0x7500
	s_addc_u32 s15, s25, 0
	v_rcp_iflag_f32_e32 v3, v3
	v_add_u32_e32 v1, s12, v1
	v_add_u32_e32 v4, 1, v1
	s_mov_b64 s[16:17], -1
	v_mul_f32_e32 v2, 0x4f7ffffe, v3
	v_cvt_u32_f32_e32 v2, v2
	v_sub_u32_e32 v3, 0, v0
	v_mul_lo_u32 v3, v3, v2
	v_mul_hi_u32 v3, v2, v3
	v_add_u32_e32 v2, v2, v3
	v_mul_hi_u32 v2, v1, v2
	v_mul_lo_u32 v3, v2, v0
	v_sub_u32_e32 v1, v1, v3
	v_add_u32_e32 v5, 1, v2
	v_cmp_ge_u32_e32 vcc, v1, v0
	v_sub_u32_e32 v3, v1, v0
	s_nop 0
	v_cndmask_b32_e32 v2, v2, v5, vcc
	v_cndmask_b32_e32 v1, v1, v3, vcc
	v_add_u32_e32 v3, 1, v2
	v_cmp_ge_u32_e32 vcc, v1, v0
	s_nop 1
	v_cndmask_b32_e32 v2, v2, v3, vcc
	v_mul_lo_u32 v1, v0, v2
	v_add_u32_e32 v0, v1, v0
	v_cmp_ne_u32_e32 vcc, v4, v0
	v_mov_b32_e32 v250, v0
	v_add_u32_e32 v251, 1, v2
	v_mov_b64_e32 v[0:1], s[14:15]
	s_and_saveexec_b64 s[12:13], vcc
	s_cbranch_execz .LBB0_146
	v_mov_b32_e32 v0, 0
	global_load_dword v1, v0, s[14:15] offset:-256 sc1
	s_mov_b64 s[20:21], 0
	s_waitcnt vmcnt(0)
	v_cmp_lt_u32_e32 vcc, v1, v250
	s_and_saveexec_b64 s[18:19], vcc
	s_cbranch_execz .LBB0_145
	s_add_u32 s16, s24, 0x4200
	s_addc_u32 s17, s25, 0
	s_mov_b32 s33, 1
	s_branch .LBB0_138

; __device__ __forceinline__ unsigned xb_ld(unsigned* p)              { return __hip_atomic_load(p, __ATOMIC_RELAXED, __HIP_MEMORY_SCOPE_AGENT); }
; #define XB_SPIN(cond, bar) do { unsigned _sp = 0; while (cond) { __builtin_amdgcn_s_sleep(1); \
;     if ((++_sp & 255u) == 0u) { if (xb_ld(&(bar)[XB_TMO])) break; if (_sp > XB_SPIN_CAP) { atomicAdd(&(bar)[XB_TMO], 1u); break; } } } } while (0)
; __device__ __forceinline__ void xcd_barrier(const XcdBarrier& b) {
;     ...
;             else XB_SPIN(xb_ld(&bar[XB_TOPGEN]) == tg, bar);
.LBB0_142:
	global_load_dword v1, v0, s[14:15] offset:-256 sc1
	s_add_i32 s33, s33, 1
	s_mov_b64 s[26:27], -1
	s_waitcnt vmcnt(0)
	v_cmp_ge_u32_e32 vcc, v1, v250
	s_orn2_b64 s[30:31], vcc, exec
	s_branch .LBB0_137

; __device__ __forceinline__ unsigned xb_ld(unsigned* p)              { return __hip_atomic_load(p, __ATOMIC_RELAXED, __HIP_MEMORY_SCOPE_AGENT); }
; __device__ __forceinline__ unsigned xb_add(unsigned* p, unsigned v) { return __hip_atomic_fetch_add(p, v, __ATOMIC_RELAXED, __HIP_MEMORY_SCOPE_AGENT); }
; #define XB_SPIN(cond, bar) do { unsigned _sp = 0; while (cond) { __builtin_amdgcn_s_sleep(1); \
;     if ((++_sp & 255u) == 0u) { if (xb_ld(&(bar)[XB_TMO])) break; if (_sp > XB_SPIN_CAP) { atomicAdd(&(bar)[XB_TMO], 1u); break; } } } } while (0)
; __device__ __forceinline__ void xcd_barrier(const XcdBarrier& b) {
;     ...
;             const unsigned og = xb_add(&bar[XB_TOP], 1u);
;             const unsigned tg = og / nx;
;             if (og + 1u == (tg + 1u) * nx) xb_add(&bar[XB_TOPGEN], 1u);
;             else XB_SPIN(xb_ld(&bar[XB_TOPGEN]) == tg, bar);
.LBB0_345:
	s_or_b64 exec, exec, s[12:13]
	v_cvt_f32_u32_e32 v3, v0
	s_waitcnt vmcnt(0)
	v_readfirstlane_b32 s10, v2
	s_add_u32 s12, s24, 0x7500
	s_addc_u32 s13, s25, 0
	v_rcp_iflag_f32_e32 v3, v3
	v_add_u32_e32 v1, s10, v1
	v_add_u32_e32 v4, 1, v1
	s_mov_b64 s[14:15], -1
	v_mul_f32_e32 v2, 0x4f7ffffe, v3
	v_cvt_u32_f32_e32 v2, v2
	v_sub_u32_e32 v3, 0, v0
	v_mul_lo_u32 v3, v3, v2
	v_mul_hi_u32 v3, v2, v3
	v_add_u32_e32 v2, v2, v3
	v_mul_hi_u32 v2, v1, v2
	v_mul_lo_u32 v3, v2, v0
	v_sub_u32_e32 v1, v1, v3
	v_add_u32_e32 v5, 1, v2
	v_cmp_ge_u32_e32 vcc, v1, v0
	v_sub_u32_e32 v3, v1, v0
	s_nop 0
	v_cndmask_b32_e32 v2, v2, v5, vcc
	v_cndmask_b32_e32 v1, v1, v3, vcc
	v_add_u32_e32 v3, 1, v2
	v_cmp_ge_u32_e32 vcc, v1, v0
	s_nop 1
	v_cndmask_b32_e32 v2, v2, v3, vcc
	v_mul_lo_u32 v1, v0, v2
	v_add_u32_e32 v0, v1, v0
	v_cmp_ne_u32_e32 vcc, v4, v0
	v_mov_b32_e32 v250, v0
	v_add_u32_e32 v251, 1, v2
	v_mov_b64_e32 v[0:1], s[12:13]
	s_and_saveexec_b64 s[10:11], vcc
	s_cbranch_execz .LBB0_357
	v_mov_b32_e32 v0, 0
	global_load_dword v1, v0, s[12:13] offset:-256 sc1
	s_mov_b64 s[18:19], 0
	s_waitcnt vmcnt(0)
	v_cmp_lt_u32_e32 vcc, v1, v250
	s_and_saveexec_b64 s[16:17], vcc
	s_cbranch_execz .LBB0_356
	s_add_u32 s14, s24, 0x4200
	s_addc_u32 s15, s25, 0
	s_mov_b32 s30, 1
	s_branch .LBB0_349

; __device__ __forceinline__ unsigned xb_ld(unsigned* p)              { return __hip_atomic_load(p, __ATOMIC_RELAXED, __HIP_MEMORY_SCOPE_AGENT); }
; #define XB_SPIN(cond, bar) do { unsigned _sp = 0; while (cond) { __builtin_amdgcn_s_sleep(1); \
;     if ((++_sp & 255u) == 0u) { if (xb_ld(&(bar)[XB_TMO])) break; if (_sp > XB_SPIN_CAP) { atomicAdd(&(bar)[XB_TMO], 1u); break; } } } } while (0)
; __device__ __forceinline__ void xcd_barrier(const XcdBarrier& b) {
;     ...
;             else XB_SPIN(xb_ld(&bar[XB_TOPGEN]) == tg, bar);
.LBB0_353:
	global_load_dword v1, v0, s[12:13] offset:-256 sc1
	s_add_i32 s30, s30, 1
	s_mov_b64 s[22:23], -1
	s_waitcnt vmcnt(0)
	v_cmp_ge_u32_e32 vcc, v1, v250
	s_orn2_b64 s[28:29], vcc, exec
	s_branch .LBB0_348

; __device__ __forceinline__ unsigned xb_ld(unsigned* p)              { return __hip_atomic_load(p, __ATOMIC_RELAXED, __HIP_MEMORY_SCOPE_AGENT); }
; __device__ __forceinline__ unsigned xb_add(unsigned* p, unsigned v) { return __hip_atomic_fetch_add(p, v, __ATOMIC_RELAXED, __HIP_MEMORY_SCOPE_AGENT); }
; #define XB_SPIN(cond, bar) do { unsigned _sp = 0; while (cond) { __builtin_amdgcn_s_sleep(1); \
;     if ((++_sp & 255u) == 0u) { if (xb_ld(&(bar)[XB_TMO])) break; if (_sp > XB_SPIN_CAP) { atomicAdd(&(bar)[XB_TMO], 1u); break; } } } } while (0)
; __device__ __forceinline__ void xcd_barrier(const XcdBarrier& b) {
;     ...
;             const unsigned og = xb_add(&bar[XB_TOP], 1u);
;             const unsigned tg = og / nx;
;             if (og + 1u == (tg + 1u) * nx) xb_add(&bar[XB_TOPGEN], 1u);
;             else XB_SPIN(xb_ld(&bar[XB_TOPGEN]) == tg, bar);
.LBB0_436:
	s_or_b64 exec, exec, s[28:29]
	s_waitcnt vmcnt(0)
	v_readfirstlane_b32 s11, v2
	v_cvt_f32_u32_e32 v2, v0
	v_sub_u32_e32 v3, 0, v0
	v_add_u32_e32 v1, s11, v1
	v_readlane_b32 s12, v247, 15
	v_rcp_iflag_f32_e32 v2, v2
	v_readlane_b32 s13, v247, 16
	s_mov_b64 s[28:29], -1
	v_mul_f32_e32 v2, 0x4f7ffffe, v2
	v_cvt_u32_f32_e32 v2, v2
	v_mul_lo_u32 v3, v3, v2
	v_mul_hi_u32 v3, v2, v3
	v_add_u32_e32 v2, v2, v3
	v_mul_hi_u32 v2, v1, v2
	v_mul_lo_u32 v3, v2, v0
	v_sub_u32_e32 v3, v1, v3
	v_cmp_ge_u32_e32 vcc, v3, v0
	v_add_u32_e32 v4, 1, v2
	v_add_u32_e32 v1, 1, v1
	v_cndmask_b32_e32 v2, v2, v4, vcc
	v_sub_u32_e32 v4, v3, v0
	v_cndmask_b32_e32 v3, v3, v4, vcc
	v_cmp_ge_u32_e32 vcc, v3, v0
	v_add_u32_e32 v3, 1, v2
	s_nop 0
	v_cndmask_b32_e32 v2, v2, v3, vcc
	v_mul_lo_u32 v3, v0, v2
	v_add_u32_e32 v0, v3, v0
	v_cmp_ne_u32_e32 vcc, v1, v0
	v_mov_b32_e32 v250, v0
	v_add_u32_e32 v251, 1, v2
	v_mov_b64_e32 v[0:1], s[12:13]
	s_and_saveexec_b64 s[22:23], vcc
	s_cbranch_execz .LBB0_448
	v_readlane_b32 s12, v247, 15
	v_readlane_b32 s13, v247, 16
	s_mov_b64 s[36:37], 0
	s_nop 3
	global_load_dword v0, v173, s[12:13] offset:-256 sc1
	s_waitcnt vmcnt(0)
	v_cmp_lt_u32_e32 vcc, v0, v250
	s_and_saveexec_b64 s[28:29], vcc
	s_cbranch_execz .LBB0_447
	s_mov_b32 s11, 1
	s_branch .LBB0_440

; __device__ __forceinline__ unsigned xb_ld(unsigned* p)              { return __hip_atomic_load(p, __ATOMIC_RELAXED, __HIP_MEMORY_SCOPE_AGENT); }
; #define XB_SPIN(cond, bar) do { unsigned _sp = 0; while (cond) { __builtin_amdgcn_s_sleep(1); \
;     if ((++_sp & 255u) == 0u) { if (xb_ld(&(bar)[XB_TMO])) break; if (_sp > XB_SPIN_CAP) { atomicAdd(&(bar)[XB_TMO], 1u); break; } } } } while (0)
; __device__ __forceinline__ void xcd_barrier(const XcdBarrier& b) {
;     ...
;             else XB_SPIN(xb_ld(&bar[XB_TOPGEN]) == tg, bar);
.LBB0_444:
	v_readlane_b32 s12, v247, 15
	v_readlane_b32 s13, v247, 16
	s_add_i32 s11, s11, 1
	s_mov_b64 s[44:45], -1
	s_nop 2
	global_load_dword v0, v173, s[12:13] offset:-256 sc1
	s_waitcnt vmcnt(0)
	v_cmp_ge_u32_e32 vcc, v0, v250
	s_orn2_b64 s[42:43], vcc, exec
	s_branch .LBB0_439

; __device__ __forceinline__ unsigned xb_ld(unsigned* p)              { return __hip_atomic_load(p, __ATOMIC_RELAXED, __HIP_MEMORY_SCOPE_AGENT); }
; __device__ __forceinline__ unsigned xb_add(unsigned* p, unsigned v) { return __hip_atomic_fetch_add(p, v, __ATOMIC_RELAXED, __HIP_MEMORY_SCOPE_AGENT); }
; #define XB_SPIN(cond, bar) do { unsigned _sp = 0; while (cond) { __builtin_amdgcn_s_sleep(1); \
;     if ((++_sp & 255u) == 0u) { if (xb_ld(&(bar)[XB_TMO])) break; if (_sp > XB_SPIN_CAP) { atomicAdd(&(bar)[XB_TMO], 1u); break; } } } } while (0)
; __device__ __forceinline__ void xcd_barrier(const XcdBarrier& b) {
;     ...
;             const unsigned og = xb_add(&bar[XB_TOP], 1u);
;             const unsigned tg = og / nx;
;             if (og + 1u == (tg + 1u) * nx) xb_add(&bar[XB_TOPGEN], 1u);
;             else XB_SPIN(xb_ld(&bar[XB_TOPGEN]) == tg, bar);
.LBB0_1406:
	s_or_b64 exec, exec, s[28:29]
	s_waitcnt vmcnt(0)
	v_readfirstlane_b32 s6, v2
	v_cvt_f32_u32_e32 v2, v0
	v_sub_u32_e32 v3, 0, v0
	v_add_u32_e32 v1, s6, v1
	v_readlane_b32 s16, v247, 15
	v_rcp_iflag_f32_e32 v2, v2
	v_readlane_b32 s17, v247, 16
	s_mov_b64 s[28:29], -1
	v_mul_f32_e32 v2, 0x4f7ffffe, v2
	v_cvt_u32_f32_e32 v2, v2
	v_mul_lo_u32 v3, v3, v2
	v_mul_hi_u32 v3, v2, v3
	v_add_u32_e32 v2, v2, v3
	v_mul_hi_u32 v2, v1, v2
	v_mul_lo_u32 v3, v2, v0
	v_sub_u32_e32 v3, v1, v3
	v_cmp_ge_u32_e32 vcc, v3, v0
	v_add_u32_e32 v4, 1, v2
	v_add_u32_e32 v1, 1, v1
	v_cndmask_b32_e32 v2, v2, v4, vcc
	v_sub_u32_e32 v4, v3, v0
	v_cndmask_b32_e32 v3, v3, v4, vcc
	v_cmp_ge_u32_e32 vcc, v3, v0
	v_add_u32_e32 v3, 1, v2
	s_nop 0
	v_cndmask_b32_e32 v2, v2, v3, vcc
	v_mul_lo_u32 v3, v0, v2
	v_add_u32_e32 v0, v3, v0
	v_cmp_ne_u32_e32 vcc, v1, v0
	v_mov_b32_e32 v250, v0
	v_add_u32_e32 v251, 1, v2
	v_mov_b64_e32 v[0:1], s[16:17]
	s_and_saveexec_b64 s[22:23], vcc
	s_cbranch_execz .LBB0_1418
	v_readlane_b32 s16, v247, 15
	v_readlane_b32 s17, v247, 16
	s_mov_b64 s[36:37], 0
	s_nop 3
	global_load_dword v0, v173, s[16:17] offset:-256 sc1
	s_waitcnt vmcnt(0)
	v_cmp_lt_u32_e32 vcc, v0, v250
	s_and_saveexec_b64 s[28:29], vcc
	s_cbranch_execz .LBB0_1417
	s_mov_b32 s6, 1
	s_branch .LBB0_1410

; __device__ __forceinline__ unsigned xb_ld(unsigned* p)              { return __hip_atomic_load(p, __ATOMIC_RELAXED, __HIP_MEMORY_SCOPE_AGENT); }
; #define XB_SPIN(cond, bar) do { unsigned _sp = 0; while (cond) { __builtin_amdgcn_s_sleep(1); \
;     if ((++_sp & 255u) == 0u) { if (xb_ld(&(bar)[XB_TMO])) break; if (_sp > XB_SPIN_CAP) { atomicAdd(&(bar)[XB_TMO], 1u); break; } } } } while (0)
; __device__ __forceinline__ void xcd_barrier(const XcdBarrier& b) {
;     ...
;             else XB_SPIN(xb_ld(&bar[XB_TOPGEN]) == tg, bar);
.LBB0_1414:
	v_readlane_b32 s16, v247, 15
	v_readlane_b32 s17, v247, 16
	s_add_i32 s6, s6, 1
	s_mov_b64 s[44:45], -1
	s_nop 2
	global_load_dword v0, v173, s[16:17] offset:-256 sc1
	s_waitcnt vmcnt(0)
	v_cmp_ge_u32_e32 vcc, v0, v250
	s_orn2_b64 s[42:43], vcc, exec
	s_branch .LBB0_1409

; __device__ __forceinline__ unsigned xb_ld(unsigned* p)              { return __hip_atomic_load(p, __ATOMIC_RELAXED, __HIP_MEMORY_SCOPE_AGENT); }
; __device__ __forceinline__ unsigned xb_add(unsigned* p, unsigned v) { return __hip_atomic_fetch_add(p, v, __ATOMIC_RELAXED, __HIP_MEMORY_SCOPE_AGENT); }
; #define XB_SPIN(cond, bar) do { unsigned _sp = 0; while (cond) { __builtin_amdgcn_s_sleep(1); \
;     if ((++_sp & 255u) == 0u) { if (xb_ld(&(bar)[XB_TMO])) break; if (_sp > XB_SPIN_CAP) { atomicAdd(&(bar)[XB_TMO], 1u); break; } } } } while (0)
; __device__ __forceinline__ void xcd_barrier(const XcdBarrier& b) {
;     ...
;             const unsigned og = xb_add(&bar[XB_TOP], 1u);
;             const unsigned tg = og / nx;
;             if (og + 1u == (tg + 1u) * nx) xb_add(&bar[XB_TOPGEN], 1u);
;             else XB_SPIN(xb_ld(&bar[XB_TOPGEN]) == tg, bar);
.LBB0_1558:
	s_or_b64 exec, exec, s[36:37]
	s_waitcnt vmcnt(0)
	v_readfirstlane_b32 s11, v2
	v_cvt_f32_u32_e32 v2, v0
	v_sub_u32_e32 v3, 0, v0
	v_add_u32_e32 v1, s11, v1
	v_readlane_b32 s12, v247, 15
	v_rcp_iflag_f32_e32 v2, v2
	v_readlane_b32 s13, v247, 16
	s_mov_b64 s[36:37], -1
	v_mul_f32_e32 v2, 0x4f7ffffe, v2
	v_cvt_u32_f32_e32 v2, v2
	v_mul_lo_u32 v3, v3, v2
	v_mul_hi_u32 v3, v2, v3
	v_add_u32_e32 v2, v2, v3
	v_mul_hi_u32 v2, v1, v2
	v_mul_lo_u32 v3, v2, v0
	v_sub_u32_e32 v3, v1, v3
	v_cmp_ge_u32_e32 vcc, v3, v0
	v_add_u32_e32 v4, 1, v2
	v_add_u32_e32 v1, 1, v1
	v_cndmask_b32_e32 v2, v2, v4, vcc
	v_sub_u32_e32 v4, v3, v0
	v_cndmask_b32_e32 v3, v3, v4, vcc
	v_cmp_ge_u32_e32 vcc, v3, v0
	v_add_u32_e32 v3, 1, v2
	s_nop 0
	v_cndmask_b32_e32 v2, v2, v3, vcc
	v_mul_lo_u32 v3, v0, v2
	v_add_u32_e32 v0, v3, v0
	v_cmp_ne_u32_e32 vcc, v1, v0
	v_mov_b32_e32 v250, v0
	v_add_u32_e32 v251, 1, v2
	v_mov_b64_e32 v[0:1], s[12:13]
	s_and_saveexec_b64 s[22:23], vcc
	s_cbranch_execz .LBB0_1570
	v_readlane_b32 s12, v247, 15
	v_readlane_b32 s13, v247, 16
	s_mov_b64 s[40:41], 0
	s_nop 3
	global_load_dword v0, v173, s[12:13] offset:-256 sc1
	s_waitcnt vmcnt(0)
	v_cmp_lt_u32_e32 vcc, v0, v250
	s_and_saveexec_b64 s[36:37], vcc
	s_cbranch_execz .LBB0_1569
	s_mov_b32 s11, 1
	s_branch .LBB0_1562

; __device__ __forceinline__ unsigned xb_ld(unsigned* p)              { return __hip_atomic_load(p, __ATOMIC_RELAXED, __HIP_MEMORY_SCOPE_AGENT); }
; #define XB_SPIN(cond, bar) do { unsigned _sp = 0; while (cond) { __builtin_amdgcn_s_sleep(1); \
;     if ((++_sp & 255u) == 0u) { if (xb_ld(&(bar)[XB_TMO])) break; if (_sp > XB_SPIN_CAP) { atomicAdd(&(bar)[XB_TMO], 1u); break; } } } } while (0)
; __device__ __forceinline__ void xcd_barrier(const XcdBarrier& b) {
;     ...
;             else XB_SPIN(xb_ld(&bar[XB_TOPGEN]) == tg, bar);
.LBB0_1566:
	v_readlane_b32 s12, v247, 15
	v_readlane_b32 s13, v247, 16
	s_add_i32 s11, s11, 1
	s_mov_b64 s[46:47], -1
	s_nop 2
	global_load_dword v0, v173, s[12:13] offset:-256 sc1
	s_waitcnt vmcnt(0)
	v_cmp_ge_u32_e32 vcc, v0, v250
	s_orn2_b64 s[44:45], vcc, exec
	s_branch .LBB0_1561

; __device__ __forceinline__ unsigned xb_ld(unsigned* p)              { return __hip_atomic_load(p, __ATOMIC_RELAXED, __HIP_MEMORY_SCOPE_AGENT); }
; __device__ __forceinline__ unsigned xb_add(unsigned* p, unsigned v) { return __hip_atomic_fetch_add(p, v, __ATOMIC_RELAXED, __HIP_MEMORY_SCOPE_AGENT); }
; #define XB_SPIN(cond, bar) do { unsigned _sp = 0; while (cond) { __builtin_amdgcn_s_sleep(1); \
;     if ((++_sp & 255u) == 0u) { if (xb_ld(&(bar)[XB_TMO])) break; if (_sp > XB_SPIN_CAP) { atomicAdd(&(bar)[XB_TMO], 1u); break; } } } } while (0)
; __device__ __forceinline__ void xcd_barrier(const XcdBarrier& b) {
;     ...
;             const unsigned og = xb_add(&bar[XB_TOP], 1u);
;             const unsigned tg = og / nx;
;             if (og + 1u == (tg + 1u) * nx) xb_add(&bar[XB_TOPGEN], 1u);
;             else XB_SPIN(xb_ld(&bar[XB_TOPGEN]) == tg, bar);
.LBB0_1668:
	s_or_b64 exec, exec, s[28:29]
	s_waitcnt vmcnt(0)
	v_readfirstlane_b32 s11, v2
	v_cvt_f32_u32_e32 v2, v0
	v_sub_u32_e32 v3, 0, v0
	v_add_u32_e32 v1, s11, v1
	v_readlane_b32 s12, v247, 15
	v_rcp_iflag_f32_e32 v2, v2
	v_readlane_b32 s13, v247, 16
	s_mov_b64 s[36:37], -1
	v_mul_f32_e32 v2, 0x4f7ffffe, v2
	v_cvt_u32_f32_e32 v2, v2
	v_mul_lo_u32 v3, v3, v2
	v_mul_hi_u32 v3, v2, v3
	v_add_u32_e32 v2, v2, v3
	v_mul_hi_u32 v2, v1, v2
	v_mul_lo_u32 v3, v2, v0
	v_sub_u32_e32 v3, v1, v3
	v_cmp_ge_u32_e32 vcc, v3, v0
	v_add_u32_e32 v4, 1, v2
	v_add_u32_e32 v1, 1, v1
	v_cndmask_b32_e32 v2, v2, v4, vcc
	v_sub_u32_e32 v4, v3, v0
	v_cndmask_b32_e32 v3, v3, v4, vcc
	v_cmp_ge_u32_e32 vcc, v3, v0
	v_add_u32_e32 v3, 1, v2
	s_nop 0
	v_cndmask_b32_e32 v2, v2, v3, vcc
	v_mul_lo_u32 v3, v0, v2
	v_add_u32_e32 v0, v3, v0
	v_cmp_ne_u32_e32 vcc, v1, v0
	v_mov_b32_e32 v250, v0
	v_add_u32_e32 v251, 1, v2
	v_mov_b64_e32 v[0:1], s[12:13]
	s_and_saveexec_b64 s[22:23], vcc
	s_cbranch_execz .LBB0_1680
	v_readlane_b32 s12, v247, 15
	v_readlane_b32 s13, v247, 16
	s_mov_b64 s[40:41], 0
	s_nop 3
	global_load_dword v0, v173, s[12:13] offset:-256 sc1
	s_waitcnt vmcnt(0)
	v_cmp_lt_u32_e32 vcc, v0, v250
	s_and_saveexec_b64 s[36:37], vcc
	s_cbranch_execz .LBB0_1679
	s_mov_b32 s11, 1
	s_branch .LBB0_1672

; __device__ __forceinline__ unsigned xb_ld(unsigned* p)              { return __hip_atomic_load(p, __ATOMIC_RELAXED, __HIP_MEMORY_SCOPE_AGENT); }
; __device__ __forceinline__ unsigned xb_add(unsigned* p, unsigned v) { return __hip_atomic_fetch_add(p, v, __ATOMIC_RELAXED, __HIP_MEMORY_SCOPE_AGENT); }
; #define XB_SPIN(cond, bar) do { unsigned _sp = 0; while (cond) { __builtin_amdgcn_s_sleep(1); \
;     if ((++_sp & 255u) == 0u) { if (xb_ld(&(bar)[XB_TMO])) break; if (_sp > XB_SPIN_CAP) { atomicAdd(&(bar)[XB_TMO], 1u); break; } } } } while (0)
; __device__ __forceinline__ void xcd_barrier(const XcdBarrier& b) {
;     ...
;             const unsigned og = xb_add(&bar[XB_TOP], 1u);
;             const unsigned tg = og / nx;
;             if (og + 1u == (tg + 1u) * nx) xb_add(&bar[XB_TOPGEN], 1u);
;             else XB_SPIN(xb_ld(&bar[XB_TOPGEN]) == tg, bar);
.LBB0_2179:
	s_or_b64 exec, exec, s[26:27]
	s_waitcnt vmcnt(0)
	v_readfirstlane_b32 s6, v2
	v_cvt_f32_u32_e32 v2, v0
	v_sub_u32_e32 v3, 0, v0
	v_add_u32_e32 v1, s6, v1
	v_readlane_b32 s14, v247, 15
	v_rcp_iflag_f32_e32 v2, v2
	v_readlane_b32 s15, v247, 16
	s_mov_b64 s[26:27], -1
	v_mul_f32_e32 v2, 0x4f7ffffe, v2
	v_cvt_u32_f32_e32 v2, v2
	v_mul_lo_u32 v3, v3, v2
	v_mul_hi_u32 v3, v2, v3
	v_add_u32_e32 v2, v2, v3
	v_mul_hi_u32 v2, v1, v2
	v_mul_lo_u32 v3, v2, v0
	v_sub_u32_e32 v3, v1, v3
	v_cmp_ge_u32_e32 vcc, v3, v0
	v_add_u32_e32 v4, 1, v2
	v_add_u32_e32 v1, 1, v1
	v_cndmask_b32_e32 v2, v2, v4, vcc
	v_sub_u32_e32 v4, v3, v0
	v_cndmask_b32_e32 v3, v3, v4, vcc
	v_cmp_ge_u32_e32 vcc, v3, v0
	v_add_u32_e32 v3, 1, v2
	s_nop 0
	v_cndmask_b32_e32 v2, v2, v3, vcc
	v_mul_lo_u32 v3, v0, v2
	v_add_u32_e32 v0, v3, v0
	v_cmp_ne_u32_e32 vcc, v1, v0
	v_mov_b32_e32 v250, v0
	v_add_u32_e32 v251, 1, v2
	v_mov_b64_e32 v[0:1], s[14:15]
	s_and_saveexec_b64 s[22:23], vcc
	s_cbranch_execz .LBB0_2191
	v_readlane_b32 s14, v247, 15
	v_readlane_b32 s15, v247, 16
	s_mov_b64 s[28:29], 0
	s_nop 3
	global_load_dword v0, v173, s[14:15] offset:-256 sc1
	s_waitcnt vmcnt(0)
	v_cmp_lt_u32_e32 vcc, v0, v250
	s_and_saveexec_b64 s[26:27], vcc
	s_cbranch_execz .LBB0_2190
	s_mov_b32 s6, 1
	s_branch .LBB0_2183

; __device__ __forceinline__ unsigned xb_ld(unsigned* p)              { return __hip_atomic_load(p, __ATOMIC_RELAXED, __HIP_MEMORY_SCOPE_AGENT); }
; #define XB_SPIN(cond, bar) do { unsigned _sp = 0; while (cond) { __builtin_amdgcn_s_sleep(1); \
;     if ((++_sp & 255u) == 0u) { if (xb_ld(&(bar)[XB_TMO])) break; if (_sp > XB_SPIN_CAP) { atomicAdd(&(bar)[XB_TMO], 1u); break; } } } } while (0)
; __device__ __forceinline__ void xcd_barrier(const XcdBarrier& b) {
;     ...
;             else XB_SPIN(xb_ld(&bar[XB_TOPGEN]) == tg, bar);
.LBB0_2187:
	v_readlane_b32 s14, v247, 15
	v_readlane_b32 s15, v247, 16
	s_add_i32 s6, s6, 1
	s_mov_b64 s[42:43], -1
	s_nop 2
	global_load_dword v0, v173, s[14:15] offset:-256 sc1
	s_waitcnt vmcnt(0)
	v_cmp_ge_u32_e32 vcc, v0, v250
	s_orn2_b64 s[40:41], vcc, exec
	s_branch .LBB0_2182

; __device__ __forceinline__ unsigned xb_ld(unsigned* p)              { return __hip_atomic_load(p, __ATOMIC_RELAXED, __HIP_MEMORY_SCOPE_AGENT); }
; __device__ __forceinline__ unsigned xb_add(unsigned* p, unsigned v) { return __hip_atomic_fetch_add(p, v, __ATOMIC_RELAXED, __HIP_MEMORY_SCOPE_AGENT); }
; #define XB_SPIN(cond, bar) do { unsigned _sp = 0; while (cond) { __builtin_amdgcn_s_sleep(1); \
;     if ((++_sp & 255u) == 0u) { if (xb_ld(&(bar)[XB_TMO])) break; if (_sp > XB_SPIN_CAP) { atomicAdd(&(bar)[XB_TMO], 1u); break; } } } } while (0)
; __device__ __forceinline__ void xcd_barrier(const XcdBarrier& b) {
;     ...
;             const unsigned og = xb_add(&bar[XB_TOP], 1u);
;             const unsigned tg = og / nx;
;             if (og + 1u == (tg + 1u) * nx) xb_add(&bar[XB_TOPGEN], 1u);
;             else XB_SPIN(xb_ld(&bar[XB_TOPGEN]) == tg, bar);
.LBB0_2275:
	s_or_b64 exec, exec, s[36:37]
	s_waitcnt vmcnt(0)
	v_readfirstlane_b32 s11, v2
	v_cvt_f32_u32_e32 v2, v0
	v_sub_u32_e32 v3, 0, v0
	v_add_u32_e32 v1, s11, v1
	v_readlane_b32 s14, v247, 15
	v_rcp_iflag_f32_e32 v2, v2
	v_readlane_b32 s15, v247, 16
	s_mov_b64 s[36:37], -1
	v_mul_f32_e32 v2, 0x4f7ffffe, v2
	v_cvt_u32_f32_e32 v2, v2
	v_mul_lo_u32 v3, v3, v2
	v_mul_hi_u32 v3, v2, v3
	v_add_u32_e32 v2, v2, v3
	v_mul_hi_u32 v2, v1, v2
	v_mul_lo_u32 v3, v2, v0
	v_sub_u32_e32 v3, v1, v3
	v_cmp_ge_u32_e32 vcc, v3, v0
	v_add_u32_e32 v4, 1, v2
	v_add_u32_e32 v1, 1, v1
	v_cndmask_b32_e32 v2, v2, v4, vcc
	v_sub_u32_e32 v4, v3, v0
	v_cndmask_b32_e32 v3, v3, v4, vcc
	v_cmp_ge_u32_e32 vcc, v3, v0
	v_add_u32_e32 v3, 1, v2
	s_nop 0
	v_cndmask_b32_e32 v2, v2, v3, vcc
	v_mul_lo_u32 v3, v0, v2
	v_add_u32_e32 v0, v3, v0
	v_cmp_ne_u32_e32 vcc, v1, v0
	v_mov_b32_e32 v250, v0
	v_add_u32_e32 v251, 1, v2
	v_mov_b64_e32 v[0:1], s[14:15]
	s_and_saveexec_b64 s[22:23], vcc
	s_cbranch_execz .LBB0_2287
	v_readlane_b32 s14, v247, 15
	v_readlane_b32 s15, v247, 16
	s_mov_b64 s[40:41], 0
	s_nop 3
	global_load_dword v0, v173, s[14:15] offset:-256 sc1
	s_waitcnt vmcnt(0)
	v_cmp_lt_u32_e32 vcc, v0, v250
	s_and_saveexec_b64 s[36:37], vcc
	s_cbranch_execz .LBB0_2286
	s_mov_b32 s11, 1
	s_branch .LBB0_2279

; __device__ __forceinline__ unsigned xb_ld(unsigned* p)              { return __hip_atomic_load(p, __ATOMIC_RELAXED, __HIP_MEMORY_SCOPE_AGENT); }
; #define XB_SPIN(cond, bar) do { unsigned _sp = 0; while (cond) { __builtin_amdgcn_s_sleep(1); \
;     if ((++_sp & 255u) == 0u) { if (xb_ld(&(bar)[XB_TMO])) break; if (_sp > XB_SPIN_CAP) { atomicAdd(&(bar)[XB_TMO], 1u); break; } } } } while (0)
; __device__ __forceinline__ void xcd_barrier(const XcdBarrier& b) {
;     ...
;             else XB_SPIN(xb_ld(&bar[XB_TOPGEN]) == tg, bar);
.LBB0_2283:
	v_readlane_b32 s14, v247, 15
	v_readlane_b32 s15, v247, 16
	s_add_i32 s11, s11, 1
	s_mov_b64 s[46:47], -1
	s_nop 2
	global_load_dword v0, v173, s[14:15] offset:-256 sc1
	s_waitcnt vmcnt(0)
	v_cmp_ge_u32_e32 vcc, v0, v250
	s_orn2_b64 s[44:45], vcc, exec
	s_branch .LBB0_2278

; __device__ __forceinline__ unsigned xb_ld(unsigned* p)              { return __hip_atomic_load(p, __ATOMIC_RELAXED, __HIP_MEMORY_SCOPE_AGENT); }
; __device__ __forceinline__ unsigned xb_add(unsigned* p, unsigned v) { return __hip_atomic_fetch_add(p, v, __ATOMIC_RELAXED, __HIP_MEMORY_SCOPE_AGENT); }
; #define XB_SPIN(cond, bar) do { unsigned _sp = 0; while (cond) { __builtin_amdgcn_s_sleep(1); \
;     if ((++_sp & 255u) == 0u) { if (xb_ld(&(bar)[XB_TMO])) break; if (_sp > XB_SPIN_CAP) { atomicAdd(&(bar)[XB_TMO], 1u); break; } } } } while (0)
; __device__ __forceinline__ void xcd_barrier(const XcdBarrier& b) {
;     ...
;             const unsigned og = xb_add(&bar[XB_TOP], 1u);
;             const unsigned tg = og / nx;
;             if (og + 1u == (tg + 1u) * nx) xb_add(&bar[XB_TOPGEN], 1u);
;             else XB_SPIN(xb_ld(&bar[XB_TOPGEN]) == tg, bar);
.LBB0_2567:
	s_or_b64 exec, exec, s[30:31]
	s_waitcnt vmcnt(0)
	v_readfirstlane_b32 s6, v2
	v_cvt_f32_u32_e32 v2, v0
	v_sub_u32_e32 v3, 0, v0
	v_add_u32_e32 v1, s6, v1
	v_readlane_b32 s16, v247, 15
	v_rcp_iflag_f32_e32 v2, v2
	v_readlane_b32 s17, v247, 16
	s_mov_b64 s[30:31], -1
	v_mul_f32_e32 v2, 0x4f7ffffe, v2
	v_cvt_u32_f32_e32 v2, v2
	v_mul_lo_u32 v3, v3, v2
	v_mul_hi_u32 v3, v2, v3
	v_add_u32_e32 v2, v2, v3
	v_mul_hi_u32 v2, v1, v2
	v_mul_lo_u32 v3, v2, v0
	v_sub_u32_e32 v3, v1, v3
	v_cmp_ge_u32_e32 vcc, v3, v0
	v_add_u32_e32 v4, 1, v2
	v_add_u32_e32 v1, 1, v1
	v_cndmask_b32_e32 v2, v2, v4, vcc
	v_sub_u32_e32 v4, v3, v0
	v_cndmask_b32_e32 v3, v3, v4, vcc
	v_cmp_ge_u32_e32 vcc, v3, v0
	v_add_u32_e32 v3, 1, v2
	s_nop 0
	v_cndmask_b32_e32 v2, v2, v3, vcc
	v_mul_lo_u32 v3, v0, v2
	v_add_u32_e32 v0, v3, v0
	v_cmp_ne_u32_e32 vcc, v1, v0
	v_mov_b32_e32 v250, v0
	v_add_u32_e32 v251, 1, v2
	v_mov_b64_e32 v[0:1], s[16:17]
	s_and_saveexec_b64 s[22:23], vcc
	s_cbranch_execz .LBB0_2579
	v_readlane_b32 s16, v247, 15
	v_readlane_b32 s17, v247, 16
	s_mov_b64 s[36:37], 0
	s_nop 3
	global_load_dword v0, v173, s[16:17] offset:-256 sc1
	s_waitcnt vmcnt(0)
	v_cmp_lt_u32_e32 vcc, v0, v250
	s_and_saveexec_b64 s[30:31], vcc
	s_cbranch_execz .LBB0_2578
	s_mov_b32 s6, 1
	s_branch .LBB0_2571

; __device__ __forceinline__ unsigned xb_ld(unsigned* p)              { return __hip_atomic_load(p, __ATOMIC_RELAXED, __HIP_MEMORY_SCOPE_AGENT); }
; __device__ __forceinline__ unsigned xb_add(unsigned* p, unsigned v) { return __hip_atomic_fetch_add(p, v, __ATOMIC_RELAXED, __HIP_MEMORY_SCOPE_AGENT); }
; #define XB_SPIN(cond, bar) do { unsigned _sp = 0; while (cond) { __builtin_amdgcn_s_sleep(1); \
;     if ((++_sp & 255u) == 0u) { if (xb_ld(&(bar)[XB_TMO])) break; if (_sp > XB_SPIN_CAP) { atomicAdd(&(bar)[XB_TMO], 1u); break; } } } } while (0)
; __device__ __forceinline__ void xcd_barrier(const XcdBarrier& b) {
;     ...
;             const unsigned og = xb_add(&bar[XB_TOP], 1u);
;             const unsigned tg = og / nx;
;             if (og + 1u == (tg + 1u) * nx) xb_add(&bar[XB_TOPGEN], 1u);
;             else XB_SPIN(xb_ld(&bar[XB_TOPGEN]) == tg, bar);
.LBB0_2635:
	s_or_b64 exec, exec, s[4:5]
	v_cvt_f32_u32_e32 v3, v0
	s_waitcnt vmcnt(0)
	v_readfirstlane_b32 s2, v2
	s_mov_b64 s[4:5], -1
	v_rcp_iflag_f32_e32 v3, v3
	v_add_u32_e32 v1, s2, v1
	v_add_u32_e32 v4, 1, v1
	v_mul_f32_e32 v2, 0x4f7ffffe, v3
	v_cvt_u32_f32_e32 v2, v2
	v_sub_u32_e32 v3, 0, v0
	v_mul_lo_u32 v3, v3, v2
	v_mul_hi_u32 v3, v2, v3
	v_add_u32_e32 v2, v2, v3
	v_mul_hi_u32 v2, v1, v2
	v_mul_lo_u32 v3, v2, v0
	v_sub_u32_e32 v1, v1, v3
	v_add_u32_e32 v5, 1, v2
	v_cmp_ge_u32_e32 vcc, v1, v0
	v_sub_u32_e32 v3, v1, v0
	s_nop 0
	v_cndmask_b32_e32 v2, v2, v5, vcc
	v_cndmask_b32_e32 v1, v1, v3, vcc
	v_add_u32_e32 v3, 1, v2
	v_cmp_ge_u32_e32 vcc, v1, v0
	s_nop 1
	v_cndmask_b32_e32 v2, v2, v3, vcc
	v_mul_lo_u32 v1, v0, v2
	v_add_u32_e32 v0, v1, v0
	v_cmp_ne_u32_e32 vcc, v4, v0
	v_mov_b32_e32 v250, v0
	v_add_u32_e32 v251, 1, v2
	v_mov_b64_e32 v[0:1], s[18:19]
	s_and_saveexec_b64 s[2:3], vcc
	s_cbranch_execz .LBB0_2647
	v_mov_b32_e32 v0, 0
	global_load_dword v1, v0, s[18:19] offset:-256 sc1
	s_mov_b64 s[6:7], 0
	s_waitcnt vmcnt(0)
	v_cmp_lt_u32_e32 vcc, v1, v250
	s_and_saveexec_b64 s[4:5], vcc
	s_cbranch_execz .LBB0_2646
	s_mov_b32 s16, 1
	s_branch .LBB0_2639

; __device__ __forceinline__ unsigned xb_ld(unsigned* p)              { return __hip_atomic_load(p, __ATOMIC_RELAXED, __HIP_MEMORY_SCOPE_AGENT); }
; #define XB_SPIN(cond, bar) do { unsigned _sp = 0; while (cond) { __builtin_amdgcn_s_sleep(1); \
;     if ((++_sp & 255u) == 0u) { if (xb_ld(&(bar)[XB_TMO])) break; if (_sp > XB_SPIN_CAP) { atomicAdd(&(bar)[XB_TMO], 1u); break; } } } } while (0)
; __device__ __forceinline__ void xcd_barrier(const XcdBarrier& b) {
;     ...
;             else XB_SPIN(xb_ld(&bar[XB_TOPGEN]) == tg, bar);
.LBB0_2643:
	global_load_dword v1, v0, s[18:19] offset:-256 sc1
	s_add_i32 s16, s16, 1
	s_mov_b64 s[10:11], -1
	s_waitcnt vmcnt(0)
	v_cmp_ge_u32_e32 vcc, v1, v250
	s_orn2_b64 s[14:15], vcc, exec
	s_branch .LBB0_2638
